# strategy 4b: mid-block s_setprio 0/1 pairs deleted in all three GEMM K-loops (one priority window per 32-MFMA block), on top of v013
# baseline (speedup 1.0000x reference)
; #define PG8_STAGE(bufoff, gbase, voff) do { _Pragma("unroll") for (int _i = 0; _i < 2; ++_i) \
;         __builtin_amdgcn_global_load_lds((const unsigned*)((const char*)(gbase) + (voff)[_i]), (PG8_LAS unsigned*)(lds + (bufoff) + ldsw + _i * 8192), 16, 0, 0); } while (0)
; #define PG8_LDA(dst, b, h) do { _Pragma("unroll") for (int m = 0; m < 4; ++m) _Pragma("unroll") for (int k = 0; k < 2; ++k) dst[m][k] = *(const PG8_LAS bf16x8*)(lds + PG8_SA(b, h) + aoff + m * 2048 + k * 1024); } while (0)
; #define PG8_LDB(dst, b, h) do { _Pragma("unroll") for (int n = 0; n < 2; ++n) _Pragma("unroll") for (int k = 0; k < 2; ++k) dst[n][k] = *(const PG8_LAS bf16x8*)(lds + PG8_SB(b, h) + boff + n * 2048 + k * 1024); } while (0)
; #define PG8_MMA(ai, bj, At, Bt) do { __builtin_amdgcn_s_setprio(1); _Pragma("unroll") for (int m = 0; m < 4; ++m) _Pragma("unroll") for (int n = 0; n < 2; ++n) _Pragma("unroll") for (int k = 0; k < 2; ++k) \
;         acc[ai][bj][m][n] = __builtin_amdgcn_mfma_f32_16x16x32_bf16(Bt[n][k], At[m][k], acc[ai][bj][m][n], 0, 0, 0); __builtin_amdgcn_s_setprio(0); } while (0)
; #define PG8_WAIT_V(n) asm volatile("s_waitcnt vmcnt(" #n ")" ::: "memory")
; #define PG8_WAIT_L(n) asm volatile("s_waitcnt lgkmcnt(" #n ")" ::: "memory")
; #define PG8_BAR __builtin_amdgcn_s_barrier()
; #define PG8_SCHED __builtin_amdgcn_sched_barrier(0)
; template <class Epi, class Sched, bool ALIGN_EPI = false, bool SP2 = false>
; __device__ __forceinline__ void gemm_phase(PG8_LAS unsigned char* lds, const Gemm g, const Sched& S, const Epi& E) {
;     ...
;             PG8_LDB(B0, 0, 0); PG8_LDB(B1, 0, 1); PG8_SCHED; PG8_LDA(At, 0, 0); PG8_STAGE(PG8_SA(1, 1), a1 + hstep, voffA);
;             PG8_WAIT_V(8); PG8_WAIT_L(0); PG8_BAR; PG8_MMA(0, 0, At, B0); PG8_MMA(0, 1, At, B1); PG8_BAR; PG8_SCHED;
;             PG8_LDA(At, 0, 1); PG8_STAGE(PG8_SB(0, 0), b2, voffB); PG8_STAGE(PG8_SB(0, 1), b2 + hstep, voffB); PG8_STAGE(PG8_SA(0, 0), a2, voffA);
;             PG8_WAIT_V(8); PG8_WAIT_L(0); PG8_BAR; PG8_MMA(1, 0, At, B0); PG8_MMA(1, 1, At, B1); PG8_BAR; PG8_SCHED;
.LBB0_581:
	s_add_u32 s5, s2, 0xfffc0080
	s_addc_u32 s8, s3, -1
	s_add_i32 s64, 0, 0x10000
	s_cmp_eq_u32 s63, 12
	s_cselect_b32 s11, s34, s8
	s_cselect_b32 s10, s35, s5
	s_cselect_b32 s9, s40, s49
	s_cselect_b32 s8, s41, s47
	s_add_i32 s5, 0, 0x14000
	v_add_u32_e32 v46, s64, v173
	v_add_u32_e32 v170, s5, v173
	ds_read_b128 v[34:37], v46
	ds_read_b128 v[38:41], v46 offset:1024
	ds_read_b128 v[42:45], v46 offset:2048
	ds_read_b128 v[46:49], v46 offset:3072
	ds_read_b128 v[166:169], v170
	ds_read_b128 v[176:179], v170 offset:1024
	ds_read_b128 v[180:183], v170 offset:2048
	ds_read_b128 v[184:187], v170 offset:3072
	v_lshl_add_u64 v[170:171], s[2:3], 0, v[162:163]
	s_add_i32 m0, s55, 0xc000
	ds_read_b128 v[188:191], v175
	ds_read_b128 v[192:195], v175 offset:1024
	ds_read_b128 v[196:199], v175 offset:2048
	ds_read_b128 v[214:217], v175 offset:3072
	ds_read_b128 v[218:221], v175 offset:4096
	ds_read_b128 v[222:225], v175 offset:5120
	ds_read_b128 v[226:229], v175 offset:6144
	ds_read_b128 v[230:233], v175 offset:7168
	global_load_lds_dwordx4 v[170:171], off
	v_lshl_add_u64 v[170:171], s[2:3], 0, v[164:165]
	s_add_i32 m0, s55, 0xe000
	s_nop 0
	global_load_lds_dwordx4 v[170:171], off
	s_waitcnt vmcnt(8)
	s_waitcnt lgkmcnt(0)
	s_barrier
	s_setprio 1
	s_waitcnt lgkmcnt(0)
	v_mfma_f32_16x16x32_bf16 v[142:145], v[34:37], v[188:191], v[142:145]
	v_mfma_f32_16x16x32_bf16 v[138:141], v[42:45], v[188:191], v[138:141]
	v_mfma_f32_16x16x32_bf16 v[126:129], v[34:37], v[196:199], v[126:129]
	v_mfma_f32_16x16x32_bf16 v[122:125], v[42:45], v[196:199], v[122:125]
	v_mfma_f32_16x16x32_bf16 v[110:113], v[34:37], v[218:221], v[110:113]
	v_mfma_f32_16x16x32_bf16 v[106:109], v[42:45], v[218:221], v[106:109]
	v_mfma_f32_16x16x32_bf16 v[94:97], v[34:37], v[226:229], v[94:97]
	v_mfma_f32_16x16x32_bf16 v[90:93], v[42:45], v[226:229], v[90:93]
	v_mfma_f32_16x16x32_bf16 v[142:145], v[38:41], v[192:195], v[142:145]
	v_mfma_f32_16x16x32_bf16 v[138:141], v[46:49], v[192:195], v[138:141]
	v_mfma_f32_16x16x32_bf16 v[126:129], v[38:41], v[214:217], v[126:129]
	v_mfma_f32_16x16x32_bf16 v[122:125], v[46:49], v[214:217], v[122:125]
	v_mfma_f32_16x16x32_bf16 v[110:113], v[38:41], v[222:225], v[110:113]
	v_mfma_f32_16x16x32_bf16 v[106:109], v[46:49], v[222:225], v[106:109]
	v_mfma_f32_16x16x32_bf16 v[94:97], v[38:41], v[230:233], v[94:97]
	v_mfma_f32_16x16x32_bf16 v[90:93], v[46:49], v[230:233], v[90:93]
	v_mfma_f32_16x16x32_bf16 v[134:137], v[166:169], v[188:191], v[134:137]
	v_mfma_f32_16x16x32_bf16 v[130:133], v[180:183], v[188:191], v[130:133]
	v_mfma_f32_16x16x32_bf16 v[118:121], v[166:169], v[196:199], v[118:121]
	v_mfma_f32_16x16x32_bf16 v[114:117], v[180:183], v[196:199], v[114:117]
	v_mfma_f32_16x16x32_bf16 v[102:105], v[166:169], v[218:221], v[102:105]
	v_mfma_f32_16x16x32_bf16 v[98:101], v[180:183], v[218:221], v[98:101]
	v_mfma_f32_16x16x32_bf16 v[86:89], v[166:169], v[226:229], v[86:89]
	v_mfma_f32_16x16x32_bf16 v[82:85], v[180:183], v[226:229], v[82:85]
	v_mfma_f32_16x16x32_bf16 v[134:137], v[176:179], v[192:195], v[134:137]
	v_mfma_f32_16x16x32_bf16 v[130:133], v[184:187], v[192:195], v[130:133]
	v_mfma_f32_16x16x32_bf16 v[118:121], v[176:179], v[214:217], v[118:121]
	v_mfma_f32_16x16x32_bf16 v[114:117], v[184:187], v[214:217], v[114:117]
	v_mfma_f32_16x16x32_bf16 v[102:105], v[176:179], v[222:225], v[102:105]
	v_mfma_f32_16x16x32_bf16 v[98:101], v[184:187], v[222:225], v[98:101]
	v_mfma_f32_16x16x32_bf16 v[86:89], v[176:179], v[230:233], v[86:89]
	v_mfma_f32_16x16x32_bf16 v[82:85], v[184:187], v[230:233], v[82:85]
	s_setprio 0
	s_barrier
	s_add_i32 s64, s64, s54
	v_lshl_add_u64 v[170:171], s[8:9], 0, v[0:1]
	s_mov_b32 m0, s64
	ds_read_b128 v[188:191], v175 offset:16384
	ds_read_b128 v[192:195], v175 offset:17408
	ds_read_b128 v[196:199], v175 offset:18432
	ds_read_b128 v[214:217], v175 offset:19456
	ds_read_b128 v[218:221], v175 offset:20480
	ds_read_b128 v[222:225], v175 offset:21504
	ds_read_b128 v[226:229], v175 offset:22528
	ds_read_b128 v[230:233], v175 offset:23552
	global_load_lds_dwordx4 v[170:171], off
	s_add_i32 m0, s64, 0x2000
	s_add_u32 s64, s8, 0x40000
	v_lshl_add_u64 v[200:201], s[8:9], 0, v[156:157]
	s_addc_u32 s65, s9, 0
	s_add_i32 s5, s5, s54
	global_load_lds_dwordx4 v[200:201], off
	v_lshl_add_u64 v[234:235], s[64:65], 0, v[0:1]
	s_mov_b32 m0, s5
	v_lshl_add_u64 v[236:237], s[10:11], 0, v[158:159]
	global_load_lds_dwordx4 v[234:235], off
	v_lshl_add_u64 v[234:235], s[64:65], 0, v[156:157]
	s_add_i32 m0, s5, 0x2000
	s_nop 0
	global_load_lds_dwordx4 v[234:235], off
	v_lshl_add_u64 v[234:235], s[10:11], 0, v[160:161]
	s_mov_b32 m0, s55
	s_nop 0
	global_load_lds_dwordx4 v[234:235], off
	s_mov_b32 m0, s56
	s_nop 0
	global_load_lds_dwordx4 v[236:237], off
	s_waitcnt vmcnt(8)
	s_waitcnt lgkmcnt(0)
	s_barrier
; #define PG8_STAGE(bufoff, gbase, voff) do { _Pragma("unroll") for (int _i = 0; _i < 2; ++_i) \
;         __builtin_amdgcn_global_load_lds((const unsigned*)((const char*)(gbase) + (voff)[_i]), (PG8_LAS unsigned*)(lds + (bufoff) + ldsw + _i * 8192), 16, 0, 0); } while (0)
; #define PG8_LDA(dst, b, h) do { _Pragma("unroll") for (int m = 0; m < 4; ++m) _Pragma("unroll") for (int k = 0; k < 2; ++k) dst[m][k] = *(const PG8_LAS bf16x8*)(lds + PG8_SA(b, h) + aoff + m * 2048 + k * 1024); } while (0)
; #define PG8_LDB(dst, b, h) do { _Pragma("unroll") for (int n = 0; n < 2; ++n) _Pragma("unroll") for (int k = 0; k < 2; ++k) dst[n][k] = *(const PG8_LAS bf16x8*)(lds + PG8_SB(b, h) + boff + n * 2048 + k * 1024); } while (0)
; #define PG8_MMA(ai, bj, At, Bt) do { __builtin_amdgcn_s_setprio(1); _Pragma("unroll") for (int m = 0; m < 4; ++m) _Pragma("unroll") for (int n = 0; n < 2; ++n) _Pragma("unroll") for (int k = 0; k < 2; ++k) \
;         acc[ai][bj][m][n] = __builtin_amdgcn_mfma_f32_16x16x32_bf16(Bt[n][k], At[m][k], acc[ai][bj][m][n], 0, 0, 0); __builtin_amdgcn_s_setprio(0); } while (0)
; #define PG8_WAIT_V(n) asm volatile("s_waitcnt vmcnt(" #n ")" ::: "memory")
; #define PG8_WAIT_L(n) asm volatile("s_waitcnt lgkmcnt(" #n ")" ::: "memory")
; #define PG8_BAR __builtin_amdgcn_s_barrier()
; #define PG8_SCHED __builtin_amdgcn_sched_barrier(0)
; template <class Epi, class Sched, bool ALIGN_EPI = false, bool SP2 = false>
; __device__ __forceinline__ void gemm_phase(PG8_LAS unsigned char* lds, const Gemm g, const Sched& S, const Epi& E) {
;     ...
;             PG8_WAIT_V(8); PG8_WAIT_L(0); PG8_BAR; PG8_MMA(1, 0, At, B0); PG8_MMA(1, 1, At, B1); PG8_BAR; PG8_SCHED;
;             PG8_LDB(B0, 1, 0); PG8_LDB(B1, 1, 1); PG8_SCHED; PG8_LDA(At, 1, 0); PG8_STAGE(PG8_SA(0, 1), a2 + hstep, voffA);
;             PG8_WAIT_V(8); PG8_WAIT_L(0); PG8_BAR; PG8_MMA(0, 0, At, B0); PG8_MMA(0, 1, At, B1); PG8_BAR; PG8_SCHED;
	s_setprio 1
	s_waitcnt lgkmcnt(0)
	v_mfma_f32_16x16x32_bf16 v[78:81], v[34:37], v[188:191], v[78:81]
	v_mfma_f32_16x16x32_bf16 v[74:77], v[42:45], v[188:191], v[74:77]
	v_mfma_f32_16x16x32_bf16 v[62:65], v[34:37], v[196:199], v[62:65]
	v_mfma_f32_16x16x32_bf16 v[58:61], v[42:45], v[196:199], v[58:61]
	v_mfma_f32_16x16x32_bf16 v[30:33], v[34:37], v[218:221], v[30:33]
	v_mfma_f32_16x16x32_bf16 v[26:29], v[42:45], v[218:221], v[26:29]
	v_mfma_f32_16x16x32_bf16 v[14:17], v[34:37], v[226:229], v[14:17]
	v_mfma_f32_16x16x32_bf16 v[10:13], v[42:45], v[226:229], v[10:13]
	v_mfma_f32_16x16x32_bf16 v[78:81], v[38:41], v[192:195], v[78:81]
	v_mfma_f32_16x16x32_bf16 v[74:77], v[46:49], v[192:195], v[74:77]
	v_mfma_f32_16x16x32_bf16 v[62:65], v[38:41], v[214:217], v[62:65]
	v_mfma_f32_16x16x32_bf16 v[58:61], v[46:49], v[214:217], v[58:61]
	v_mfma_f32_16x16x32_bf16 v[30:33], v[38:41], v[222:225], v[30:33]
	v_mfma_f32_16x16x32_bf16 v[26:29], v[46:49], v[222:225], v[26:29]
	v_mfma_f32_16x16x32_bf16 v[14:17], v[38:41], v[230:233], v[14:17]
	v_mfma_f32_16x16x32_bf16 v[10:13], v[46:49], v[230:233], v[10:13]
	v_mfma_f32_16x16x32_bf16 v[22:25], v[166:169], v[218:221], v[22:25]
	v_mfma_f32_16x16x32_bf16 v[18:21], v[180:183], v[218:221], v[18:21]
	v_mfma_f32_16x16x32_bf16 v[6:9], v[166:169], v[226:229], v[6:9]
	v_mfma_f32_16x16x32_bf16 v[2:5], v[180:183], v[226:229], v[2:5]
	v_mfma_f32_16x16x32_bf16 v[34:37], v[166:169], v[188:191], v[70:73]
	v_mfma_f32_16x16x32_bf16 v[38:41], v[180:183], v[188:191], v[66:69]
	v_mfma_f32_16x16x32_bf16 v[42:45], v[166:169], v[196:199], v[54:57]
	v_mfma_f32_16x16x32_bf16 v[46:49], v[180:183], v[196:199], v[50:53]
	v_mfma_f32_16x16x32_bf16 v[22:25], v[176:179], v[222:225], v[22:25]
	v_mfma_f32_16x16x32_bf16 v[18:21], v[184:187], v[222:225], v[18:21]
	v_mfma_f32_16x16x32_bf16 v[6:9], v[176:179], v[230:233], v[6:9]
	v_mfma_f32_16x16x32_bf16 v[2:5], v[184:187], v[230:233], v[2:5]
	v_mfma_f32_16x16x32_bf16 v[34:37], v[176:179], v[192:195], v[34:37]
	v_mfma_f32_16x16x32_bf16 v[38:41], v[184:187], v[192:195], v[38:41]
	v_mfma_f32_16x16x32_bf16 v[42:45], v[176:179], v[214:217], v[42:45]
	v_mfma_f32_16x16x32_bf16 v[46:49], v[184:187], v[214:217], v[46:49]
	s_setprio 0
	s_barrier
	s_add_i32 s5, 0, 0x18000
	v_add_u32_e32 v70, s5, v173
	v_add_u32_e32 v184, s29, v173
	ds_read_b128 v[50:53], v70
	ds_read_b128 v[54:57], v70 offset:1024
	ds_read_b128 v[66:69], v70 offset:2048
	ds_read_b128 v[70:73], v70 offset:3072
	ds_read_b128 v[166:169], v184
	ds_read_b128 v[176:179], v184 offset:1024
	ds_read_b128 v[180:183], v184 offset:2048
	ds_read_b128 v[184:187], v184 offset:3072
	s_add_u32 s10, s10, 0x40000
	s_addc_u32 s11, s11, 0
	s_mov_b32 m0, s57
	v_lshl_add_u64 v[238:239], s[10:11], 0, v[160:161]
	ds_read_b128 v[188:191], v175 offset:32768
	ds_read_b128 v[192:195], v175 offset:33792
	ds_read_b128 v[196:199], v175 offset:34816
	ds_read_b128 v[214:217], v175 offset:35840
	ds_read_b128 v[218:221], v175 offset:36864
	ds_read_b128 v[222:225], v175 offset:37888
	ds_read_b128 v[226:229], v175 offset:38912
	ds_read_b128 v[230:233], v175 offset:39936
	global_load_lds_dwordx4 v[238:239], off
	v_lshl_add_u64 v[238:239], s[10:11], 0, v[158:159]
	s_mov_b32 m0, s58
	s_nop 0
	global_load_lds_dwordx4 v[238:239], off
	s_waitcnt vmcnt(8)
	s_waitcnt lgkmcnt(0)
	s_barrier
	s_setprio 1
	s_waitcnt lgkmcnt(0)
	v_mfma_f32_16x16x32_bf16 v[142:145], v[50:53], v[188:191], v[142:145]
	v_mfma_f32_16x16x32_bf16 v[138:141], v[66:69], v[188:191], v[138:141]
	v_mfma_f32_16x16x32_bf16 v[126:129], v[50:53], v[196:199], v[126:129]
	v_mfma_f32_16x16x32_bf16 v[122:125], v[66:69], v[196:199], v[122:125]
	v_mfma_f32_16x16x32_bf16 v[110:113], v[50:53], v[218:221], v[110:113]
	v_mfma_f32_16x16x32_bf16 v[106:109], v[66:69], v[218:221], v[106:109]
	v_mfma_f32_16x16x32_bf16 v[94:97], v[50:53], v[226:229], v[94:97]
	v_mfma_f32_16x16x32_bf16 v[90:93], v[66:69], v[226:229], v[90:93]
	v_mfma_f32_16x16x32_bf16 v[142:145], v[54:57], v[192:195], v[142:145]
	v_mfma_f32_16x16x32_bf16 v[138:141], v[70:73], v[192:195], v[138:141]
	v_mfma_f32_16x16x32_bf16 v[126:129], v[54:57], v[214:217], v[126:129]
	v_mfma_f32_16x16x32_bf16 v[122:125], v[70:73], v[214:217], v[122:125]
	v_mfma_f32_16x16x32_bf16 v[110:113], v[54:57], v[222:225], v[110:113]
	v_mfma_f32_16x16x32_bf16 v[106:109], v[70:73], v[222:225], v[106:109]
	v_mfma_f32_16x16x32_bf16 v[94:97], v[54:57], v[230:233], v[94:97]
	v_mfma_f32_16x16x32_bf16 v[90:93], v[70:73], v[230:233], v[90:93]
	v_mfma_f32_16x16x32_bf16 v[134:137], v[166:169], v[188:191], v[134:137]
	v_mfma_f32_16x16x32_bf16 v[130:133], v[180:183], v[188:191], v[130:133]
	v_mfma_f32_16x16x32_bf16 v[118:121], v[166:169], v[196:199], v[118:121]
	v_mfma_f32_16x16x32_bf16 v[114:117], v[180:183], v[196:199], v[114:117]
	v_mfma_f32_16x16x32_bf16 v[102:105], v[166:169], v[218:221], v[102:105]
	v_mfma_f32_16x16x32_bf16 v[98:101], v[180:183], v[218:221], v[98:101]
	v_mfma_f32_16x16x32_bf16 v[86:89], v[166:169], v[226:229], v[86:89]
	v_mfma_f32_16x16x32_bf16 v[82:85], v[180:183], v[226:229], v[82:85]
	v_mfma_f32_16x16x32_bf16 v[134:137], v[176:179], v[192:195], v[134:137]
	v_mfma_f32_16x16x32_bf16 v[130:133], v[184:187], v[192:195], v[130:133]
	v_mfma_f32_16x16x32_bf16 v[118:121], v[176:179], v[214:217], v[118:121]
	v_mfma_f32_16x16x32_bf16 v[114:117], v[184:187], v[214:217], v[114:117]
	v_mfma_f32_16x16x32_bf16 v[102:105], v[176:179], v[222:225], v[102:105]
	v_mfma_f32_16x16x32_bf16 v[98:101], v[184:187], v[222:225], v[98:101]
	v_mfma_f32_16x16x32_bf16 v[86:89], v[176:179], v[230:233], v[86:89]
	v_mfma_f32_16x16x32_bf16 v[82:85], v[184:187], v[230:233], v[82:85]
	s_setprio 0
	s_barrier
; #define PG8_STAGE(bufoff, gbase, voff) do { _Pragma("unroll") for (int _i = 0; _i < 2; ++_i) \
;         __builtin_amdgcn_global_load_lds((const unsigned*)((const char*)(gbase) + (voff)[_i]), (PG8_LAS unsigned*)(lds + (bufoff) + ldsw + _i * 8192), 16, 0, 0); } while (0)
; #define PG8_LDA(dst, b, h) do { _Pragma("unroll") for (int m = 0; m < 4; ++m) _Pragma("unroll") for (int k = 0; k < 2; ++k) dst[m][k] = *(const PG8_LAS bf16x8*)(lds + PG8_SA(b, h) + aoff + m * 2048 + k * 1024); } while (0)
; #define PG8_MMA(ai, bj, At, Bt) do { __builtin_amdgcn_s_setprio(1); _Pragma("unroll") for (int m = 0; m < 4; ++m) _Pragma("unroll") for (int n = 0; n < 2; ++n) _Pragma("unroll") for (int k = 0; k < 2; ++k) \
;         acc[ai][bj][m][n] = __builtin_amdgcn_mfma_f32_16x16x32_bf16(Bt[n][k], At[m][k], acc[ai][bj][m][n], 0, 0, 0); __builtin_amdgcn_s_setprio(0); } while (0)
; #define PG8_WAIT_V(n) asm volatile("s_waitcnt vmcnt(" #n ")" ::: "memory")
; #define PG8_WAIT_L(n) asm volatile("s_waitcnt lgkmcnt(" #n ")" ::: "memory")
; #define PG8_BAR __builtin_amdgcn_s_barrier()
; #define PG8_SCHED __builtin_amdgcn_sched_barrier(0)
; template <class Epi, class Sched, bool ALIGN_EPI = false, bool SP2 = false>
; __device__ __forceinline__ void gemm_phase(PG8_LAS unsigned char* lds, const Gemm g, const Sched& S, const Epi& E) {
;     ...
;         for (int t = 0; t < nt; t += 2) {
;     ...
;             PG8_LDA(At, 1, 1); PG8_STAGE(PG8_SB(1, 0), b3, voffB); PG8_STAGE(PG8_SB(1, 1), b3 + hstep, voffB); PG8_STAGE(PG8_SA(1, 0), a3, voffA);
;             PG8_WAIT_V(8); PG8_WAIT_L(0); PG8_BAR; PG8_MMA(1, 0, At, B0); PG8_MMA(1, 1, At, B1); PG8_BAR; PG8_SCHED;
	s_add_i32 s5, s5, s54
	v_lshl_add_u64 v[170:171], v[170:171], 0, s[30:31]
	s_mov_b32 m0, s5
	ds_read_b128 v[188:191], v175 offset:49152
	ds_read_b128 v[192:195], v175 offset:50176
	ds_read_b128 v[196:199], v175 offset:51200
	ds_read_b128 v[214:217], v175 offset:52224
	ds_read_b128 v[218:221], v175 offset:53248
	ds_read_b128 v[222:225], v175 offset:54272
	ds_read_b128 v[226:229], v175 offset:55296
	ds_read_b128 v[230:233], v175 offset:56320
	global_load_lds_dwordx4 v[170:171], off
	s_add_i32 m0, s5, 0x2000
	s_add_u32 s8, s8, 0x40080
	v_lshl_add_u64 v[170:171], v[200:201], 0, s[30:31]
	s_addc_u32 s9, s9, 0
	s_add_i32 s5, s29, s54
	global_load_lds_dwordx4 v[170:171], off
	v_lshl_add_u64 v[170:171], s[8:9], 0, v[0:1]
	s_mov_b32 m0, s5
	s_nop 0
	global_load_lds_dwordx4 v[170:171], off
	v_lshl_add_u64 v[170:171], s[8:9], 0, v[156:157]
	s_add_i32 m0, s5, 0x2000
	s_nop 0
	global_load_lds_dwordx4 v[170:171], off
	v_lshl_add_u64 v[170:171], v[234:235], 0, s[30:31]
	s_mov_b32 m0, s60
	s_nop 0
	global_load_lds_dwordx4 v[170:171], off
	v_lshl_add_u64 v[170:171], v[236:237], 0, s[30:31]
	s_mov_b32 m0, s61
	s_nop 0
	global_load_lds_dwordx4 v[170:171], off
	s_waitcnt vmcnt(8)
	s_waitcnt lgkmcnt(0)
	s_barrier
	s_setprio 1
	s_waitcnt lgkmcnt(0)
	v_mfma_f32_16x16x32_bf16 v[78:81], v[50:53], v[188:191], v[78:81]
	v_mfma_f32_16x16x32_bf16 v[74:77], v[66:69], v[188:191], v[74:77]
	v_mfma_f32_16x16x32_bf16 v[62:65], v[50:53], v[196:199], v[62:65]
	v_mfma_f32_16x16x32_bf16 v[58:61], v[66:69], v[196:199], v[58:61]
	v_mfma_f32_16x16x32_bf16 v[30:33], v[50:53], v[218:221], v[30:33]
	v_mfma_f32_16x16x32_bf16 v[26:29], v[66:69], v[218:221], v[26:29]
	v_mfma_f32_16x16x32_bf16 v[14:17], v[50:53], v[226:229], v[14:17]
	v_mfma_f32_16x16x32_bf16 v[10:13], v[66:69], v[226:229], v[10:13]
	v_mfma_f32_16x16x32_bf16 v[78:81], v[54:57], v[192:195], v[78:81]
	v_mfma_f32_16x16x32_bf16 v[74:77], v[70:73], v[192:195], v[74:77]
	v_mfma_f32_16x16x32_bf16 v[62:65], v[54:57], v[214:217], v[62:65]
	v_mfma_f32_16x16x32_bf16 v[58:61], v[70:73], v[214:217], v[58:61]
	v_mfma_f32_16x16x32_bf16 v[30:33], v[54:57], v[222:225], v[30:33]
	v_mfma_f32_16x16x32_bf16 v[26:29], v[70:73], v[222:225], v[26:29]
	v_mfma_f32_16x16x32_bf16 v[14:17], v[54:57], v[230:233], v[14:17]
	v_mfma_f32_16x16x32_bf16 v[10:13], v[70:73], v[230:233], v[10:13]
	v_mfma_f32_16x16x32_bf16 v[34:37], v[166:169], v[188:191], v[34:37]
	v_mfma_f32_16x16x32_bf16 v[70:73], v[176:179], v[192:195], v[34:37]
	v_mfma_f32_16x16x32_bf16 v[34:37], v[180:183], v[188:191], v[38:41]
	v_mfma_f32_16x16x32_bf16 v[66:69], v[184:187], v[192:195], v[34:37]
	v_mfma_f32_16x16x32_bf16 v[34:37], v[166:169], v[196:199], v[42:45]
	v_mfma_f32_16x16x32_bf16 v[54:57], v[176:179], v[214:217], v[34:37]
	v_mfma_f32_16x16x32_bf16 v[34:37], v[180:183], v[196:199], v[46:49]
	v_mfma_f32_16x16x32_bf16 v[22:25], v[166:169], v[218:221], v[22:25]
	v_mfma_f32_16x16x32_bf16 v[18:21], v[180:183], v[218:221], v[18:21]
	v_mfma_f32_16x16x32_bf16 v[6:9], v[166:169], v[226:229], v[6:9]
	v_mfma_f32_16x16x32_bf16 v[2:5], v[180:183], v[226:229], v[2:5]
	v_mfma_f32_16x16x32_bf16 v[50:53], v[184:187], v[214:217], v[34:37]
	v_mfma_f32_16x16x32_bf16 v[22:25], v[176:179], v[222:225], v[22:25]
	v_mfma_f32_16x16x32_bf16 v[18:21], v[184:187], v[222:225], v[18:21]
	v_mfma_f32_16x16x32_bf16 v[6:9], v[176:179], v[230:233], v[6:9]
	v_mfma_f32_16x16x32_bf16 v[2:5], v[184:187], v[230:233], v[2:5]
	s_setprio 0
	s_barrier
	s_add_i32 s63, s63, 2
	s_add_u32 s2, s2, 0x100
	s_addc_u32 s3, s3, 0
	s_add_u32 s47, s47, 0x100
	s_addc_u32 s49, s49, 0
	s_cmp_gt_u32 s63, 13
	s_cbranch_scc0 .LBB0_581
	s_and_b64 vcc, exec, s[44:45]
	s_cbranch_vccz .LBB0_584
	s_barrier

; #define PG8_STAGE(bufoff, gbase, voff) do { _Pragma("unroll") for (int _i = 0; _i < 2; ++_i) \
;         __builtin_amdgcn_global_load_lds((const unsigned*)((const char*)(gbase) + (voff)[_i]), (PG8_LAS unsigned*)(lds + (bufoff) + ldsw + _i * 8192), 16, 0, 0); } while (0)
; #define PG8_LDA(dst, b, h) do { _Pragma("unroll") for (int m = 0; m < 4; ++m) _Pragma("unroll") for (int k = 0; k < 2; ++k) dst[m][k] = *(const PG8_LAS bf16x8*)(lds + PG8_SA(b, h) + aoff + m * 2048 + k * 1024); } while (0)
; #define PG8_LDB(dst, b, h) do { _Pragma("unroll") for (int n = 0; n < 2; ++n) _Pragma("unroll") for (int k = 0; k < 2; ++k) dst[n][k] = *(const PG8_LAS bf16x8*)(lds + PG8_SB(b, h) + boff + n * 2048 + k * 1024); } while (0)
; #define PG8_MMA(ai, bj, At, Bt) do { __builtin_amdgcn_s_setprio(1); _Pragma("unroll") for (int m = 0; m < 4; ++m) _Pragma("unroll") for (int n = 0; n < 2; ++n) _Pragma("unroll") for (int k = 0; k < 2; ++k) \
;         acc[ai][bj][m][n] = __builtin_amdgcn_mfma_f32_16x16x32_bf16(Bt[n][k], At[m][k], acc[ai][bj][m][n], 0, 0, 0); __builtin_amdgcn_s_setprio(0); } while (0)
; #define PG8_WAIT_V(n) asm volatile("s_waitcnt vmcnt(" #n ")" ::: "memory")
; #define PG8_BAR __builtin_amdgcn_s_barrier()
; template <class Epi, class Sched, bool ALIGN_EPI = false, bool SP2 = false>
; __device__ __forceinline__ void gemm_phase(PG8_LAS unsigned char* lds, const Gemm g, const Sched& S, const Epi& E) {
;     ...
;         for (int t = 0; t < nt; t += 2) {
;             const bool last = (t == nt - 2);
;             const char* a1 = cA + (size_t)(t + 1) * kstep;
;             const char* a2 = last ? nA : cA + (size_t)(t + 2) * kstep; const char* b2 = last ? nB : cB + (size_t)(t + 2) * kstep;
;             const char* a3 = a2 + kstep; const char* b3 = b2 + kstep;
;             if (last && has_next) S.a_ready(nxt);
;             if constexpr (SP2) {
;             PG8_LDB(B0, 0, 0); PG8_LDB(B1, 0, 1); PG8_SCHED; PG8_LDA(At, 0, 0); PG8_STAGE(PG8_SA(1, 1), a1 + hstep, voffA);
;             PG8_WAIT_V(8); PG8_WAIT_L(0); PG8_BAR; PG8_MMA(0, 0, At, B0); PG8_MMA(0, 1, At, B1); PG8_BAR; PG8_SCHED;
;             PG8_LDA(At, 0, 1); PG8_STAGE(PG8_SB(0, 0), b2, voffB); PG8_STAGE(PG8_SB(0, 1), b2 + hstep, voffB); PG8_STAGE(PG8_SA(0, 0), a2, voffA);
;             PG8_WAIT_V(8); PG8_WAIT_L(0); PG8_BAR; PG8_MMA(1, 0, At, B0); PG8_MMA(1, 1, At, B1); PG8_BAR; PG8_SCHED;
.LBB0_639:
	s_add_i32 s73, s10, 2
	s_add_u32 s4, s2, 0x80
	s_addc_u32 s5, s3, 0
	s_add_i32 s76, 0, 0x10000
	s_cmp_eq_u32 s66, s10
	s_cselect_b32 s11, s37, s5
	s_cselect_b32 s10, s36, s4
	s_cselect_b32 s75, s53, s72
	s_cselect_b32 s74, s52, s34
	s_add_i32 s4, 0, 0x14000
	v_add_u32_e32 v168, s76, v157
	v_add_u32_e32 v184, s4, v157
	ds_read_b128 v[142:145], v168
	ds_read_b128 v[160:163], v168 offset:1024
	ds_read_b128 v[164:167], v168 offset:2048
	ds_read_b128 v[168:171], v168 offset:3072
	ds_read_b128 v[172:175], v184
	ds_read_b128 v[176:179], v184 offset:1024
	ds_read_b128 v[180:183], v184 offset:2048
	ds_read_b128 v[184:187], v184 offset:3072
	v_lshl_add_u64 v[200:201], s[2:3], 0, v[138:139]
	s_add_i32 m0, s60, 0xc000
	ds_read_b128 v[188:191], v159
	ds_read_b128 v[192:195], v159 offset:1024
	ds_read_b128 v[196:199], v159 offset:2048
	ds_read_b128 v[214:217], v159 offset:3072
	ds_read_b128 v[218:221], v159 offset:4096
	ds_read_b128 v[222:225], v159 offset:5120
	ds_read_b128 v[226:229], v159 offset:6144
	ds_read_b128 v[230:233], v159 offset:7168
	global_load_lds_dwordx4 v[200:201], off
	v_lshl_add_u64 v[200:201], s[2:3], 0, v[140:141]
	s_add_i32 m0, s60, 0xe000
	s_nop 0
	global_load_lds_dwordx4 v[200:201], off
	s_waitcnt vmcnt(8)
	s_waitcnt lgkmcnt(0)
	s_barrier
	s_setprio 1
	s_waitcnt lgkmcnt(0)
	v_mfma_f32_16x16x32_bf16 v[126:129], v[142:145], v[188:191], v[126:129]
	v_mfma_f32_16x16x32_bf16 v[122:125], v[164:167], v[188:191], v[122:125]
	v_mfma_f32_16x16x32_bf16 v[118:121], v[142:145], v[196:199], v[118:121]
	v_mfma_f32_16x16x32_bf16 v[110:113], v[164:167], v[196:199], v[110:113]
	v_mfma_f32_16x16x32_bf16 v[102:105], v[142:145], v[218:221], v[102:105]
	v_mfma_f32_16x16x32_bf16 v[94:97], v[164:167], v[218:221], v[94:97]
	v_mfma_f32_16x16x32_bf16 v[86:89], v[142:145], v[226:229], v[86:89]
	v_mfma_f32_16x16x32_bf16 v[78:81], v[164:167], v[226:229], v[78:81]
	v_mfma_f32_16x16x32_bf16 v[126:129], v[160:163], v[192:195], v[126:129]
	v_mfma_f32_16x16x32_bf16 v[122:125], v[168:171], v[192:195], v[122:125]
	v_mfma_f32_16x16x32_bf16 v[118:121], v[160:163], v[214:217], v[118:121]
	v_mfma_f32_16x16x32_bf16 v[110:113], v[168:171], v[214:217], v[110:113]
	v_mfma_f32_16x16x32_bf16 v[102:105], v[160:163], v[222:225], v[102:105]
	v_mfma_f32_16x16x32_bf16 v[94:97], v[168:171], v[222:225], v[94:97]
	v_mfma_f32_16x16x32_bf16 v[86:89], v[160:163], v[230:233], v[86:89]
	v_mfma_f32_16x16x32_bf16 v[78:81], v[168:171], v[230:233], v[78:81]
	v_mfma_f32_16x16x32_bf16 v[114:117], v[172:175], v[188:191], v[114:117]
	v_mfma_f32_16x16x32_bf16 v[106:109], v[180:183], v[188:191], v[106:109]
	v_mfma_f32_16x16x32_bf16 v[98:101], v[172:175], v[196:199], v[98:101]
	v_mfma_f32_16x16x32_bf16 v[90:93], v[180:183], v[196:199], v[90:93]
	v_mfma_f32_16x16x32_bf16 v[82:85], v[172:175], v[218:221], v[82:85]
	v_mfma_f32_16x16x32_bf16 v[74:77], v[180:183], v[218:221], v[74:77]
	v_mfma_f32_16x16x32_bf16 v[70:73], v[172:175], v[226:229], v[70:73]
	v_mfma_f32_16x16x32_bf16 v[66:69], v[180:183], v[226:229], v[66:69]
	v_mfma_f32_16x16x32_bf16 v[114:117], v[176:179], v[192:195], v[114:117]
	v_mfma_f32_16x16x32_bf16 v[106:109], v[184:187], v[192:195], v[106:109]
	v_mfma_f32_16x16x32_bf16 v[98:101], v[176:179], v[214:217], v[98:101]
	v_mfma_f32_16x16x32_bf16 v[90:93], v[184:187], v[214:217], v[90:93]
	v_mfma_f32_16x16x32_bf16 v[82:85], v[176:179], v[222:225], v[82:85]
	v_mfma_f32_16x16x32_bf16 v[74:77], v[184:187], v[222:225], v[74:77]
	v_mfma_f32_16x16x32_bf16 v[70:73], v[176:179], v[230:233], v[70:73]
	v_mfma_f32_16x16x32_bf16 v[66:69], v[184:187], v[230:233], v[66:69]
	s_setprio 0
	s_barrier
	s_add_i32 s5, s76, s55
	v_lshl_add_u64 v[200:201], s[74:75], 0, v[0:1]
	s_mov_b32 m0, s5
	ds_read_b128 v[188:191], v159 offset:16384
	ds_read_b128 v[192:195], v159 offset:17408
	ds_read_b128 v[196:199], v159 offset:18432
	ds_read_b128 v[214:217], v159 offset:19456
	ds_read_b128 v[218:221], v159 offset:20480
	ds_read_b128 v[222:225], v159 offset:21504
	ds_read_b128 v[226:229], v159 offset:22528
	ds_read_b128 v[230:233], v159 offset:23552
	global_load_lds_dwordx4 v[200:201], off
	s_add_i32 m0, s5, 0x2000
	v_lshl_add_u64 v[234:235], s[74:75], 0, v[130:131]
	s_add_u32 s74, s74, s78
	s_addc_u32 s75, s75, 0
	s_add_i32 s4, s4, s55
	global_load_lds_dwordx4 v[234:235], off
	v_lshl_add_u64 v[236:237], s[74:75], 0, v[0:1]
	s_mov_b32 m0, s4
	v_lshl_add_u64 v[238:239], s[74:75], 0, v[130:131]
	global_load_lds_dwordx4 v[236:237], off
	s_add_i32 m0, s4, 0x2000
	v_lshl_add_u64 v[240:241], s[10:11], 0, v[134:135]
	global_load_lds_dwordx4 v[238:239], off
	s_mov_b32 m0, s60
	v_lshl_add_u64 v[242:243], s[10:11], 0, v[132:133]
	global_load_lds_dwordx4 v[240:241], off
	s_mov_b32 m0, s61
	s_nop 0
	global_load_lds_dwordx4 v[242:243], off
	s_waitcnt vmcnt(8)
	s_waitcnt lgkmcnt(0)
	s_barrier
; #define PG8_STAGE(bufoff, gbase, voff) do { _Pragma("unroll") for (int _i = 0; _i < 2; ++_i) \
;         __builtin_amdgcn_global_load_lds((const unsigned*)((const char*)(gbase) + (voff)[_i]), (PG8_LAS unsigned*)(lds + (bufoff) + ldsw + _i * 8192), 16, 0, 0); } while (0)
; #define PG8_LDA(dst, b, h) do { _Pragma("unroll") for (int m = 0; m < 4; ++m) _Pragma("unroll") for (int k = 0; k < 2; ++k) dst[m][k] = *(const PG8_LAS bf16x8*)(lds + PG8_SA(b, h) + aoff + m * 2048 + k * 1024); } while (0)
; #define PG8_LDB(dst, b, h) do { _Pragma("unroll") for (int n = 0; n < 2; ++n) _Pragma("unroll") for (int k = 0; k < 2; ++k) dst[n][k] = *(const PG8_LAS bf16x8*)(lds + PG8_SB(b, h) + boff + n * 2048 + k * 1024); } while (0)
; #define PG8_MMA(ai, bj, At, Bt) do { __builtin_amdgcn_s_setprio(1); _Pragma("unroll") for (int m = 0; m < 4; ++m) _Pragma("unroll") for (int n = 0; n < 2; ++n) _Pragma("unroll") for (int k = 0; k < 2; ++k) \
;         acc[ai][bj][m][n] = __builtin_amdgcn_mfma_f32_16x16x32_bf16(Bt[n][k], At[m][k], acc[ai][bj][m][n], 0, 0, 0); __builtin_amdgcn_s_setprio(0); } while (0)
; #define PG8_WAIT_V(n) asm volatile("s_waitcnt vmcnt(" #n ")" ::: "memory")
; #define PG8_WAIT_L(n) asm volatile("s_waitcnt lgkmcnt(" #n ")" ::: "memory")
; #define PG8_BAR __builtin_amdgcn_s_barrier()
; #define PG8_SCHED __builtin_amdgcn_sched_barrier(0)
; template <class Epi, class Sched, bool ALIGN_EPI = false, bool SP2 = false>
; __device__ __forceinline__ void gemm_phase(PG8_LAS unsigned char* lds, const Gemm g, const Sched& S, const Epi& E) {
;     ...
;             PG8_WAIT_V(8); PG8_WAIT_L(0); PG8_BAR; PG8_MMA(1, 0, At, B0); PG8_MMA(1, 1, At, B1); PG8_BAR; PG8_SCHED;
;             PG8_LDB(B0, 1, 0); PG8_LDB(B1, 1, 1); PG8_SCHED; PG8_LDA(At, 1, 0); PG8_STAGE(PG8_SA(0, 1), a2 + hstep, voffA);
;             PG8_WAIT_V(8); PG8_WAIT_L(0); PG8_BAR; PG8_MMA(0, 0, At, B0); PG8_MMA(0, 1, At, B1); PG8_BAR; PG8_SCHED;
	s_setprio 1
	s_waitcnt lgkmcnt(0)
	v_mfma_f32_16x16x32_bf16 v[62:65], v[142:145], v[188:191], v[62:65]
	v_mfma_f32_16x16x32_bf16 v[58:61], v[164:167], v[188:191], v[58:61]
	v_mfma_f32_16x16x32_bf16 v[54:57], v[142:145], v[196:199], v[54:57]
	v_mfma_f32_16x16x32_bf16 v[46:49], v[164:167], v[196:199], v[46:49]
	v_mfma_f32_16x16x32_bf16 v[38:41], v[142:145], v[218:221], v[38:41]
	v_mfma_f32_16x16x32_bf16 v[30:33], v[164:167], v[218:221], v[30:33]
	v_mfma_f32_16x16x32_bf16 v[22:25], v[142:145], v[226:229], v[22:25]
	v_mfma_f32_16x16x32_bf16 v[14:17], v[164:167], v[226:229], v[14:17]
	v_mfma_f32_16x16x32_bf16 v[62:65], v[160:163], v[192:195], v[62:65]
	v_mfma_f32_16x16x32_bf16 v[58:61], v[168:171], v[192:195], v[58:61]
	v_mfma_f32_16x16x32_bf16 v[54:57], v[160:163], v[214:217], v[54:57]
	v_mfma_f32_16x16x32_bf16 v[46:49], v[168:171], v[214:217], v[46:49]
	v_mfma_f32_16x16x32_bf16 v[38:41], v[160:163], v[222:225], v[38:41]
	v_mfma_f32_16x16x32_bf16 v[30:33], v[168:171], v[222:225], v[30:33]
	v_mfma_f32_16x16x32_bf16 v[22:25], v[160:163], v[230:233], v[22:25]
	v_mfma_f32_16x16x32_bf16 v[14:17], v[168:171], v[230:233], v[14:17]
	v_mfma_f32_16x16x32_bf16 v[50:53], v[172:175], v[188:191], v[50:53]
	v_mfma_f32_16x16x32_bf16 v[42:45], v[180:183], v[188:191], v[42:45]
	v_mfma_f32_16x16x32_bf16 v[34:37], v[172:175], v[196:199], v[34:37]
	v_mfma_f32_16x16x32_bf16 v[26:29], v[180:183], v[196:199], v[26:29]
	v_mfma_f32_16x16x32_bf16 v[18:21], v[172:175], v[218:221], v[18:21]
	v_mfma_f32_16x16x32_bf16 v[10:13], v[180:183], v[218:221], v[10:13]
	v_mfma_f32_16x16x32_bf16 v[6:9], v[172:175], v[226:229], v[6:9]
	v_mfma_f32_16x16x32_bf16 v[2:5], v[180:183], v[226:229], v[2:5]
	v_mfma_f32_16x16x32_bf16 v[50:53], v[176:179], v[192:195], v[50:53]
	v_mfma_f32_16x16x32_bf16 v[42:45], v[184:187], v[192:195], v[42:45]
	v_mfma_f32_16x16x32_bf16 v[34:37], v[176:179], v[214:217], v[34:37]
	v_mfma_f32_16x16x32_bf16 v[26:29], v[184:187], v[214:217], v[26:29]
	v_mfma_f32_16x16x32_bf16 v[18:21], v[176:179], v[222:225], v[18:21]
	v_mfma_f32_16x16x32_bf16 v[10:13], v[184:187], v[222:225], v[10:13]
	v_mfma_f32_16x16x32_bf16 v[6:9], v[176:179], v[230:233], v[6:9]
	v_mfma_f32_16x16x32_bf16 v[2:5], v[184:187], v[230:233], v[2:5]
	s_setprio 0
	s_barrier
	s_add_i32 s4, 0, 0x18000
	v_add_u32_e32 v168, s4, v157
	v_add_u32_e32 v184, s29, v157
	ds_read_b128 v[142:145], v168
	ds_read_b128 v[160:163], v168 offset:1024
	ds_read_b128 v[164:167], v168 offset:2048
	ds_read_b128 v[168:171], v168 offset:3072
	ds_read_b128 v[172:175], v184
	ds_read_b128 v[176:179], v184 offset:1024
	ds_read_b128 v[180:183], v184 offset:2048
	ds_read_b128 v[184:187], v184 offset:3072
	s_add_u32 s10, s10, s78
	s_addc_u32 s11, s11, 0
	s_mov_b32 m0, s62
	v_lshl_add_u64 v[244:245], s[10:11], 0, v[134:135]
	ds_read_b128 v[188:191], v159 offset:32768
	ds_read_b128 v[192:195], v159 offset:33792
	ds_read_b128 v[196:199], v159 offset:34816
	ds_read_b128 v[214:217], v159 offset:35840
	ds_read_b128 v[218:221], v159 offset:36864
	ds_read_b128 v[222:225], v159 offset:37888
	ds_read_b128 v[226:229], v159 offset:38912
	ds_read_b128 v[230:233], v159 offset:39936
	global_load_lds_dwordx4 v[244:245], off
	v_lshl_add_u64 v[244:245], s[10:11], 0, v[132:133]
	s_mov_b32 m0, s63
	s_nop 0
	global_load_lds_dwordx4 v[244:245], off
	s_waitcnt vmcnt(8)
	s_waitcnt lgkmcnt(0)
	s_barrier
	s_setprio 1
	s_waitcnt lgkmcnt(0)
	v_mfma_f32_16x16x32_bf16 v[126:129], v[142:145], v[188:191], v[126:129]
	v_mfma_f32_16x16x32_bf16 v[122:125], v[164:167], v[188:191], v[122:125]
	v_mfma_f32_16x16x32_bf16 v[118:121], v[142:145], v[196:199], v[118:121]
	v_mfma_f32_16x16x32_bf16 v[110:113], v[164:167], v[196:199], v[110:113]
	v_mfma_f32_16x16x32_bf16 v[102:105], v[142:145], v[218:221], v[102:105]
	v_mfma_f32_16x16x32_bf16 v[94:97], v[164:167], v[218:221], v[94:97]
	v_mfma_f32_16x16x32_bf16 v[86:89], v[142:145], v[226:229], v[86:89]
	v_mfma_f32_16x16x32_bf16 v[78:81], v[164:167], v[226:229], v[78:81]
	v_mfma_f32_16x16x32_bf16 v[126:129], v[160:163], v[192:195], v[126:129]
	v_mfma_f32_16x16x32_bf16 v[122:125], v[168:171], v[192:195], v[122:125]
	v_mfma_f32_16x16x32_bf16 v[118:121], v[160:163], v[214:217], v[118:121]
	v_mfma_f32_16x16x32_bf16 v[110:113], v[168:171], v[214:217], v[110:113]
	v_mfma_f32_16x16x32_bf16 v[102:105], v[160:163], v[222:225], v[102:105]
	v_mfma_f32_16x16x32_bf16 v[94:97], v[168:171], v[222:225], v[94:97]
	v_mfma_f32_16x16x32_bf16 v[86:89], v[160:163], v[230:233], v[86:89]
	v_mfma_f32_16x16x32_bf16 v[78:81], v[168:171], v[230:233], v[78:81]
	v_mfma_f32_16x16x32_bf16 v[114:117], v[172:175], v[188:191], v[114:117]
	v_mfma_f32_16x16x32_bf16 v[106:109], v[180:183], v[188:191], v[106:109]
	v_mfma_f32_16x16x32_bf16 v[98:101], v[172:175], v[196:199], v[98:101]
	v_mfma_f32_16x16x32_bf16 v[90:93], v[180:183], v[196:199], v[90:93]
	v_mfma_f32_16x16x32_bf16 v[82:85], v[172:175], v[218:221], v[82:85]
	v_mfma_f32_16x16x32_bf16 v[74:77], v[180:183], v[218:221], v[74:77]
	v_mfma_f32_16x16x32_bf16 v[70:73], v[172:175], v[226:229], v[70:73]
	v_mfma_f32_16x16x32_bf16 v[66:69], v[180:183], v[226:229], v[66:69]
	v_mfma_f32_16x16x32_bf16 v[114:117], v[176:179], v[192:195], v[114:117]
	v_mfma_f32_16x16x32_bf16 v[106:109], v[184:187], v[192:195], v[106:109]
	v_mfma_f32_16x16x32_bf16 v[98:101], v[176:179], v[214:217], v[98:101]
	v_mfma_f32_16x16x32_bf16 v[90:93], v[184:187], v[214:217], v[90:93]
	v_mfma_f32_16x16x32_bf16 v[82:85], v[176:179], v[222:225], v[82:85]
	v_mfma_f32_16x16x32_bf16 v[74:77], v[184:187], v[222:225], v[74:77]
	v_mfma_f32_16x16x32_bf16 v[70:73], v[176:179], v[230:233], v[70:73]
	v_mfma_f32_16x16x32_bf16 v[66:69], v[184:187], v[230:233], v[66:69]
	s_setprio 0
	s_barrier
; #define PG8_STAGE(bufoff, gbase, voff) do { _Pragma("unroll") for (int _i = 0; _i < 2; ++_i) \
;         __builtin_amdgcn_global_load_lds((const unsigned*)((const char*)(gbase) + (voff)[_i]), (PG8_LAS unsigned*)(lds + (bufoff) + ldsw + _i * 8192), 16, 0, 0); } while (0)
; #define PG8_LDA(dst, b, h) do { _Pragma("unroll") for (int m = 0; m < 4; ++m) _Pragma("unroll") for (int k = 0; k < 2; ++k) dst[m][k] = *(const PG8_LAS bf16x8*)(lds + PG8_SA(b, h) + aoff + m * 2048 + k * 1024); } while (0)
; #define PG8_MMA(ai, bj, At, Bt) do { __builtin_amdgcn_s_setprio(1); _Pragma("unroll") for (int m = 0; m < 4; ++m) _Pragma("unroll") for (int n = 0; n < 2; ++n) _Pragma("unroll") for (int k = 0; k < 2; ++k) \
;         acc[ai][bj][m][n] = __builtin_amdgcn_mfma_f32_16x16x32_bf16(Bt[n][k], At[m][k], acc[ai][bj][m][n], 0, 0, 0); __builtin_amdgcn_s_setprio(0); } while (0)
; #define PG8_WAIT_V(n) asm volatile("s_waitcnt vmcnt(" #n ")" ::: "memory")
; #define PG8_WAIT_L(n) asm volatile("s_waitcnt lgkmcnt(" #n ")" ::: "memory")
; #define PG8_BAR __builtin_amdgcn_s_barrier()
; #define PG8_SCHED __builtin_amdgcn_sched_barrier(0)
; template <class Epi, class Sched, bool ALIGN_EPI = false, bool SP2 = false>
; __device__ __forceinline__ void gemm_phase(PG8_LAS unsigned char* lds, const Gemm g, const Sched& S, const Epi& E) {
;     ...
;         for (int t = 0; t < nt; t += 2) {
;     ...
;             PG8_LDA(At, 1, 1); PG8_STAGE(PG8_SB(1, 0), b3, voffB); PG8_STAGE(PG8_SB(1, 1), b3 + hstep, voffB); PG8_STAGE(PG8_SA(1, 0), a3, voffA);
;             PG8_WAIT_V(8); PG8_WAIT_L(0); PG8_BAR; PG8_MMA(1, 0, At, B0); PG8_MMA(1, 1, At, B1); PG8_BAR; PG8_SCHED;
	s_add_i32 s4, s4, s55
	v_lshl_add_u64 v[200:201], v[200:201], 0, s[30:31]
	s_mov_b32 m0, s4
	ds_read_b128 v[188:191], v159 offset:49152
	ds_read_b128 v[192:195], v159 offset:50176
	ds_read_b128 v[196:199], v159 offset:51200
	ds_read_b128 v[214:217], v159 offset:52224
	ds_read_b128 v[218:221], v159 offset:53248
	ds_read_b128 v[222:225], v159 offset:54272
	ds_read_b128 v[226:229], v159 offset:55296
	ds_read_b128 v[230:233], v159 offset:56320
	global_load_lds_dwordx4 v[200:201], off
	v_lshl_add_u64 v[200:201], v[234:235], 0, s[30:31]
	s_add_i32 m0, s4, 0x2000
	s_add_i32 s4, s29, s55
	global_load_lds_dwordx4 v[200:201], off
	v_lshl_add_u64 v[200:201], v[236:237], 0, s[30:31]
	s_mov_b32 m0, s4
	s_nop 0
	global_load_lds_dwordx4 v[200:201], off
	v_lshl_add_u64 v[200:201], v[238:239], 0, s[30:31]
	s_add_i32 m0, s4, 0x2000
	s_nop 0
	global_load_lds_dwordx4 v[200:201], off
	v_lshl_add_u64 v[200:201], v[240:241], 0, s[30:31]
	s_mov_b32 m0, s33
	s_nop 0
	global_load_lds_dwordx4 v[200:201], off
	v_lshl_add_u64 v[200:201], v[242:243], 0, s[30:31]
	s_mov_b32 m0, s65
	s_nop 0
	global_load_lds_dwordx4 v[200:201], off
	s_waitcnt vmcnt(8)
	s_waitcnt lgkmcnt(0)
	s_barrier
	s_setprio 1
	s_waitcnt lgkmcnt(0)
	v_mfma_f32_16x16x32_bf16 v[62:65], v[142:145], v[188:191], v[62:65]
	v_mfma_f32_16x16x32_bf16 v[58:61], v[164:167], v[188:191], v[58:61]
	v_mfma_f32_16x16x32_bf16 v[54:57], v[142:145], v[196:199], v[54:57]
	v_mfma_f32_16x16x32_bf16 v[46:49], v[164:167], v[196:199], v[46:49]
	v_mfma_f32_16x16x32_bf16 v[38:41], v[142:145], v[218:221], v[38:41]
	v_mfma_f32_16x16x32_bf16 v[30:33], v[164:167], v[218:221], v[30:33]
	v_mfma_f32_16x16x32_bf16 v[22:25], v[142:145], v[226:229], v[22:25]
	v_mfma_f32_16x16x32_bf16 v[14:17], v[164:167], v[226:229], v[14:17]
	v_mfma_f32_16x16x32_bf16 v[62:65], v[160:163], v[192:195], v[62:65]
	v_mfma_f32_16x16x32_bf16 v[58:61], v[168:171], v[192:195], v[58:61]
	v_mfma_f32_16x16x32_bf16 v[54:57], v[160:163], v[214:217], v[54:57]
	v_mfma_f32_16x16x32_bf16 v[46:49], v[168:171], v[214:217], v[46:49]
	v_mfma_f32_16x16x32_bf16 v[38:41], v[160:163], v[222:225], v[38:41]
	v_mfma_f32_16x16x32_bf16 v[30:33], v[168:171], v[222:225], v[30:33]
	v_mfma_f32_16x16x32_bf16 v[22:25], v[160:163], v[230:233], v[22:25]
	v_mfma_f32_16x16x32_bf16 v[14:17], v[168:171], v[230:233], v[14:17]
	v_mfma_f32_16x16x32_bf16 v[50:53], v[172:175], v[188:191], v[50:53]
	v_mfma_f32_16x16x32_bf16 v[42:45], v[180:183], v[188:191], v[42:45]
	v_mfma_f32_16x16x32_bf16 v[34:37], v[172:175], v[196:199], v[34:37]
	v_mfma_f32_16x16x32_bf16 v[26:29], v[180:183], v[196:199], v[26:29]
	v_mfma_f32_16x16x32_bf16 v[18:21], v[172:175], v[218:221], v[18:21]
	v_mfma_f32_16x16x32_bf16 v[10:13], v[180:183], v[218:221], v[10:13]
	v_mfma_f32_16x16x32_bf16 v[6:9], v[172:175], v[226:229], v[6:9]
	v_mfma_f32_16x16x32_bf16 v[2:5], v[180:183], v[226:229], v[2:5]
	v_mfma_f32_16x16x32_bf16 v[50:53], v[176:179], v[192:195], v[50:53]
	v_mfma_f32_16x16x32_bf16 v[42:45], v[184:187], v[192:195], v[42:45]
	v_mfma_f32_16x16x32_bf16 v[34:37], v[176:179], v[214:217], v[34:37]
	v_mfma_f32_16x16x32_bf16 v[26:29], v[184:187], v[214:217], v[26:29]
	v_mfma_f32_16x16x32_bf16 v[18:21], v[176:179], v[222:225], v[18:21]
	v_mfma_f32_16x16x32_bf16 v[10:13], v[184:187], v[222:225], v[10:13]
	v_mfma_f32_16x16x32_bf16 v[6:9], v[176:179], v[230:233], v[6:9]
	v_mfma_f32_16x16x32_bf16 v[2:5], v[184:187], v[230:233], v[2:5]
	s_setprio 0
	s_barrier
	s_add_u32 s2, s2, 0x100
	s_addc_u32 s3, s3, 0
	s_add_u32 s34, s34, 0x100
	s_addc_u32 s72, s72, 0
	s_cmp_ge_u32 s73, s64
	s_mov_b32 s10, s73
	s_cbranch_scc0 .LBB0_639
	s_and_b64 vcc, exec, s[8:9]
	s_cbranch_vccz .LBB0_642
	s_barrier

; #define PG8_STAGE(bufoff, gbase, voff) do { _Pragma("unroll") for (int _i = 0; _i < 2; ++_i) \
;         __builtin_amdgcn_global_load_lds((const unsigned*)((const char*)(gbase) + (voff)[_i]), (PG8_LAS unsigned*)(lds + (bufoff) + ldsw + _i * 8192), 16, 0, 0); } while (0)
; #define PG8_LDA(dst, b, h) do { _Pragma("unroll") for (int m = 0; m < 4; ++m) _Pragma("unroll") for (int k = 0; k < 2; ++k) dst[m][k] = *(const PG8_LAS bf16x8*)(lds + PG8_SA(b, h) + aoff + m * 2048 + k * 1024); } while (0)
; #define PG8_LDB(dst, b, h) do { _Pragma("unroll") for (int n = 0; n < 2; ++n) _Pragma("unroll") for (int k = 0; k < 2; ++k) dst[n][k] = *(const PG8_LAS bf16x8*)(lds + PG8_SB(b, h) + boff + n * 2048 + k * 1024); } while (0)
; #define PG8_MMA(ai, bj, At, Bt) do { __builtin_amdgcn_s_setprio(1); _Pragma("unroll") for (int m = 0; m < 4; ++m) _Pragma("unroll") for (int n = 0; n < 2; ++n) _Pragma("unroll") for (int k = 0; k < 2; ++k) \
;         acc[ai][bj][m][n] = __builtin_amdgcn_mfma_f32_16x16x32_bf16(Bt[n][k], At[m][k], acc[ai][bj][m][n], 0, 0, 0); __builtin_amdgcn_s_setprio(0); } while (0)
; #define PG8_WAIT_V(n) asm volatile("s_waitcnt vmcnt(" #n ")" ::: "memory")
; #define PG8_WAIT_L(n) asm volatile("s_waitcnt lgkmcnt(" #n ")" ::: "memory")
; template <class Epi, class Sched, bool ALIGN_EPI = false, bool SP2 = false>
; __device__ __forceinline__ void gemm_phase(PG8_LAS unsigned char* lds, const Gemm g, const Sched& S, const Epi& E) {
;     ...
;             const bool last = (t == nt - 2);
;             const char* a1 = cA + (size_t)(t + 1) * kstep;
;             const char* a2 = last ? nA : cA + (size_t)(t + 2) * kstep; const char* b2 = last ? nB : cB + (size_t)(t + 2) * kstep;
;             const char* a3 = a2 + kstep; const char* b3 = b2 + kstep;
;             if (last && has_next) S.a_ready(nxt);
;             if constexpr (SP2) {
;             PG8_LDB(B0, 0, 0); PG8_LDB(B1, 0, 1); PG8_SCHED; PG8_LDA(At, 0, 0); PG8_STAGE(PG8_SA(1, 1), a1 + hstep, voffA);
;             PG8_WAIT_V(8); PG8_WAIT_L(0); PG8_BAR; PG8_MMA(0, 0, At, B0); PG8_MMA(0, 1, At, B1); PG8_BAR; PG8_SCHED;
;             PG8_LDA(At, 0, 1); PG8_STAGE(PG8_SB(0, 0), b2, voffB); PG8_STAGE(PG8_SB(0, 1), b2 + hstep, voffB); PG8_STAGE(PG8_SA(0, 0), a2, voffA);
;             PG8_WAIT_V(8); PG8_WAIT_L(0); PG8_BAR; PG8_MMA(1, 0, At, B0); PG8_MMA(1, 1, At, B1); PG8_BAR; PG8_SCHED;
.LBB0_663:
	s_add_u32 s5, s2, 0xfffc0080
	s_addc_u32 s8, s3, -1
	s_add_i32 s59, 0, 0x10000
	s_cmp_eq_u32 s58, 12
	s_cselect_b32 s11, s43, s8
	s_cselect_b32 s10, s54, s5
	s_cselect_b32 s9, s41, s57
	s_cselect_b32 s8, s55, s56
	s_add_i32 s5, 0, 0x14000
	v_add_u32_e32 v166, s59, v145
	v_add_u32_e32 v182, s5, v145
	ds_read_b128 v[140:143], v166
	ds_read_b128 v[158:161], v166 offset:1024
	ds_read_b128 v[162:165], v166 offset:2048
	ds_read_b128 v[166:169], v166 offset:3072
	ds_read_b128 v[170:173], v182
	ds_read_b128 v[174:177], v182 offset:1024
	ds_read_b128 v[178:181], v182 offset:2048
	ds_read_b128 v[182:185], v182 offset:3072
	v_lshl_add_u64 v[230:231], s[2:3], 0, v[136:137]
	s_add_i32 m0, s35, 0xc000
	ds_read_b128 v[186:189], v157
	ds_read_b128 v[190:193], v157 offset:1024
	ds_read_b128 v[194:197], v157 offset:2048
	ds_read_b128 v[198:201], v157 offset:3072
	ds_read_b128 v[214:217], v157 offset:4096
	ds_read_b128 v[218:221], v157 offset:5120
	ds_read_b128 v[222:225], v157 offset:6144
	ds_read_b128 v[226:229], v157 offset:7168
	global_load_lds_dwordx4 v[230:231], off
	v_lshl_add_u64 v[230:231], s[2:3], 0, v[138:139]
	s_add_i32 m0, s35, 0xe000
	s_nop 0
	global_load_lds_dwordx4 v[230:231], off
	s_waitcnt vmcnt(8)
	s_waitcnt lgkmcnt(0)
	s_barrier
	s_setprio 1
	s_waitcnt lgkmcnt(0)
	v_mfma_f32_16x16x32_bf16 v[126:129], v[140:143], v[186:189], v[126:129]
	v_mfma_f32_16x16x32_bf16 v[118:121], v[162:165], v[186:189], v[118:121]
	v_mfma_f32_16x16x32_bf16 v[110:113], v[140:143], v[194:197], v[110:113]
	v_mfma_f32_16x16x32_bf16 v[102:105], v[162:165], v[194:197], v[102:105]
	v_mfma_f32_16x16x32_bf16 v[94:97], v[140:143], v[214:217], v[94:97]
	v_mfma_f32_16x16x32_bf16 v[86:89], v[162:165], v[214:217], v[86:89]
	v_mfma_f32_16x16x32_bf16 v[78:81], v[140:143], v[222:225], v[78:81]
	v_mfma_f32_16x16x32_bf16 v[70:73], v[162:165], v[222:225], v[70:73]
	v_mfma_f32_16x16x32_bf16 v[126:129], v[158:161], v[190:193], v[126:129]
	v_mfma_f32_16x16x32_bf16 v[118:121], v[166:169], v[190:193], v[118:121]
	v_mfma_f32_16x16x32_bf16 v[110:113], v[158:161], v[198:201], v[110:113]
	v_mfma_f32_16x16x32_bf16 v[102:105], v[166:169], v[198:201], v[102:105]
	v_mfma_f32_16x16x32_bf16 v[94:97], v[158:161], v[218:221], v[94:97]
	v_mfma_f32_16x16x32_bf16 v[86:89], v[166:169], v[218:221], v[86:89]
	v_mfma_f32_16x16x32_bf16 v[78:81], v[158:161], v[226:229], v[78:81]
	v_mfma_f32_16x16x32_bf16 v[70:73], v[166:169], v[226:229], v[70:73]
	v_mfma_f32_16x16x32_bf16 v[122:125], v[170:173], v[186:189], v[122:125]
	v_mfma_f32_16x16x32_bf16 v[114:117], v[178:181], v[186:189], v[114:117]
	v_mfma_f32_16x16x32_bf16 v[106:109], v[170:173], v[194:197], v[106:109]
	v_mfma_f32_16x16x32_bf16 v[98:101], v[178:181], v[194:197], v[98:101]
	v_mfma_f32_16x16x32_bf16 v[90:93], v[170:173], v[214:217], v[90:93]
	v_mfma_f32_16x16x32_bf16 v[82:85], v[178:181], v[214:217], v[82:85]
	v_mfma_f32_16x16x32_bf16 v[74:77], v[170:173], v[222:225], v[74:77]
	v_mfma_f32_16x16x32_bf16 v[66:69], v[178:181], v[222:225], v[66:69]
	v_mfma_f32_16x16x32_bf16 v[122:125], v[174:177], v[190:193], v[122:125]
	v_mfma_f32_16x16x32_bf16 v[114:117], v[182:185], v[190:193], v[114:117]
	v_mfma_f32_16x16x32_bf16 v[106:109], v[174:177], v[198:201], v[106:109]
	v_mfma_f32_16x16x32_bf16 v[98:101], v[182:185], v[198:201], v[98:101]
	v_mfma_f32_16x16x32_bf16 v[90:93], v[174:177], v[218:221], v[90:93]
	v_mfma_f32_16x16x32_bf16 v[82:85], v[182:185], v[218:221], v[82:85]
	v_mfma_f32_16x16x32_bf16 v[74:77], v[174:177], v[226:229], v[74:77]
	v_mfma_f32_16x16x32_bf16 v[66:69], v[182:185], v[226:229], v[66:69]
	s_setprio 0
	s_barrier
	s_add_i32 s59, s59, s4
	v_lshl_add_u64 v[230:231], s[8:9], 0, v[0:1]
	s_mov_b32 m0, s59
	ds_read_b128 v[186:189], v157 offset:16384
	ds_read_b128 v[190:193], v157 offset:17408
	ds_read_b128 v[194:197], v157 offset:18432
	ds_read_b128 v[198:201], v157 offset:19456
	ds_read_b128 v[214:217], v157 offset:20480
	ds_read_b128 v[218:221], v157 offset:21504
	ds_read_b128 v[222:225], v157 offset:22528
	ds_read_b128 v[226:229], v157 offset:23552
	global_load_lds_dwordx4 v[230:231], off
	s_add_i32 m0, s59, 0x2000
	s_add_u32 s60, s8, 0x40000
	v_lshl_add_u64 v[232:233], s[8:9], 0, v[130:131]
	s_addc_u32 s61, s9, 0
	s_add_i32 s5, s5, s4
	global_load_lds_dwordx4 v[232:233], off
	v_lshl_add_u64 v[234:235], s[60:61], 0, v[0:1]
	s_mov_b32 m0, s5
	v_lshl_add_u64 v[236:237], s[10:11], 0, v[132:133]
	global_load_lds_dwordx4 v[234:235], off
	v_lshl_add_u64 v[234:235], s[60:61], 0, v[130:131]
	s_add_i32 m0, s5, 0x2000
	s_nop 0
	global_load_lds_dwordx4 v[234:235], off
	v_lshl_add_u64 v[234:235], s[10:11], 0, v[134:135]
	s_mov_b32 m0, s35
	s_nop 0
	global_load_lds_dwordx4 v[234:235], off
	s_mov_b32 m0, s48
	s_nop 0
	global_load_lds_dwordx4 v[236:237], off
	s_waitcnt vmcnt(8)
	s_waitcnt lgkmcnt(0)
	s_barrier
; #define PG8_STAGE(bufoff, gbase, voff) do { _Pragma("unroll") for (int _i = 0; _i < 2; ++_i) \
;         __builtin_amdgcn_global_load_lds((const unsigned*)((const char*)(gbase) + (voff)[_i]), (PG8_LAS unsigned*)(lds + (bufoff) + ldsw + _i * 8192), 16, 0, 0); } while (0)
; #define PG8_LDA(dst, b, h) do { _Pragma("unroll") for (int m = 0; m < 4; ++m) _Pragma("unroll") for (int k = 0; k < 2; ++k) dst[m][k] = *(const PG8_LAS bf16x8*)(lds + PG8_SA(b, h) + aoff + m * 2048 + k * 1024); } while (0)
; #define PG8_LDB(dst, b, h) do { _Pragma("unroll") for (int n = 0; n < 2; ++n) _Pragma("unroll") for (int k = 0; k < 2; ++k) dst[n][k] = *(const PG8_LAS bf16x8*)(lds + PG8_SB(b, h) + boff + n * 2048 + k * 1024); } while (0)
; #define PG8_MMA(ai, bj, At, Bt) do { __builtin_amdgcn_s_setprio(1); _Pragma("unroll") for (int m = 0; m < 4; ++m) _Pragma("unroll") for (int n = 0; n < 2; ++n) _Pragma("unroll") for (int k = 0; k < 2; ++k) \
;         acc[ai][bj][m][n] = __builtin_amdgcn_mfma_f32_16x16x32_bf16(Bt[n][k], At[m][k], acc[ai][bj][m][n], 0, 0, 0); __builtin_amdgcn_s_setprio(0); } while (0)
; #define PG8_WAIT_V(n) asm volatile("s_waitcnt vmcnt(" #n ")" ::: "memory")
; #define PG8_WAIT_L(n) asm volatile("s_waitcnt lgkmcnt(" #n ")" ::: "memory")
; #define PG8_BAR __builtin_amdgcn_s_barrier()
; #define PG8_SCHED __builtin_amdgcn_sched_barrier(0)
; template <class Epi, class Sched, bool ALIGN_EPI = false, bool SP2 = false>
; __device__ __forceinline__ void gemm_phase(PG8_LAS unsigned char* lds, const Gemm g, const Sched& S, const Epi& E) {
;     ...
;             PG8_WAIT_V(8); PG8_WAIT_L(0); PG8_BAR; PG8_MMA(1, 0, At, B0); PG8_MMA(1, 1, At, B1); PG8_BAR; PG8_SCHED;
;             PG8_LDB(B0, 1, 0); PG8_LDB(B1, 1, 1); PG8_SCHED; PG8_LDA(At, 1, 0); PG8_STAGE(PG8_SA(0, 1), a2 + hstep, voffA);
;             PG8_WAIT_V(8); PG8_WAIT_L(0); PG8_BAR; PG8_MMA(0, 0, At, B0); PG8_MMA(0, 1, At, B1); PG8_BAR; PG8_SCHED;
	s_setprio 1
	s_waitcnt lgkmcnt(0)
	v_mfma_f32_16x16x32_bf16 v[62:65], v[140:143], v[186:189], v[62:65]
	v_mfma_f32_16x16x32_bf16 v[54:57], v[162:165], v[186:189], v[54:57]
	v_mfma_f32_16x16x32_bf16 v[46:49], v[140:143], v[194:197], v[46:49]
	v_mfma_f32_16x16x32_bf16 v[38:41], v[162:165], v[194:197], v[38:41]
	v_mfma_f32_16x16x32_bf16 v[30:33], v[140:143], v[214:217], v[30:33]
	v_mfma_f32_16x16x32_bf16 v[22:25], v[162:165], v[214:217], v[22:25]
	v_mfma_f32_16x16x32_bf16 v[14:17], v[140:143], v[222:225], v[14:17]
	v_mfma_f32_16x16x32_bf16 v[6:9], v[162:165], v[222:225], v[6:9]
	v_mfma_f32_16x16x32_bf16 v[62:65], v[158:161], v[190:193], v[62:65]
	v_mfma_f32_16x16x32_bf16 v[54:57], v[166:169], v[190:193], v[54:57]
	v_mfma_f32_16x16x32_bf16 v[46:49], v[158:161], v[198:201], v[46:49]
	v_mfma_f32_16x16x32_bf16 v[38:41], v[166:169], v[198:201], v[38:41]
	v_mfma_f32_16x16x32_bf16 v[30:33], v[158:161], v[218:221], v[30:33]
	v_mfma_f32_16x16x32_bf16 v[22:25], v[166:169], v[218:221], v[22:25]
	v_mfma_f32_16x16x32_bf16 v[14:17], v[158:161], v[226:229], v[14:17]
	v_mfma_f32_16x16x32_bf16 v[6:9], v[166:169], v[226:229], v[6:9]
	v_mfma_f32_16x16x32_bf16 v[58:61], v[170:173], v[186:189], v[58:61]
	v_mfma_f32_16x16x32_bf16 v[50:53], v[178:181], v[186:189], v[50:53]
	v_mfma_f32_16x16x32_bf16 v[42:45], v[170:173], v[194:197], v[42:45]
	v_mfma_f32_16x16x32_bf16 v[34:37], v[178:181], v[194:197], v[34:37]
	v_mfma_f32_16x16x32_bf16 v[26:29], v[170:173], v[214:217], v[26:29]
	v_mfma_f32_16x16x32_bf16 v[18:21], v[178:181], v[214:217], v[18:21]
	v_mfma_f32_16x16x32_bf16 v[10:13], v[170:173], v[222:225], v[10:13]
	v_mfma_f32_16x16x32_bf16 v[2:5], v[178:181], v[222:225], v[2:5]
	v_mfma_f32_16x16x32_bf16 v[58:61], v[174:177], v[190:193], v[58:61]
	v_mfma_f32_16x16x32_bf16 v[50:53], v[182:185], v[190:193], v[50:53]
	v_mfma_f32_16x16x32_bf16 v[42:45], v[174:177], v[198:201], v[42:45]
	v_mfma_f32_16x16x32_bf16 v[34:37], v[182:185], v[198:201], v[34:37]
	v_mfma_f32_16x16x32_bf16 v[26:29], v[174:177], v[218:221], v[26:29]
	v_mfma_f32_16x16x32_bf16 v[18:21], v[182:185], v[218:221], v[18:21]
	v_mfma_f32_16x16x32_bf16 v[10:13], v[174:177], v[226:229], v[10:13]
	v_mfma_f32_16x16x32_bf16 v[2:5], v[182:185], v[226:229], v[2:5]
	s_setprio 0
	s_barrier
	s_add_i32 s5, 0, 0x18000
	v_add_u32_e32 v166, s5, v145
	v_add_u32_e32 v182, s29, v145
	ds_read_b128 v[140:143], v166
	ds_read_b128 v[158:161], v166 offset:1024
	ds_read_b128 v[162:165], v166 offset:2048
	ds_read_b128 v[166:169], v166 offset:3072
	ds_read_b128 v[170:173], v182
	ds_read_b128 v[174:177], v182 offset:1024
	ds_read_b128 v[178:181], v182 offset:2048
	ds_read_b128 v[182:185], v182 offset:3072
	s_add_u32 s10, s10, 0x40000
	s_addc_u32 s11, s11, 0
	s_mov_b32 m0, s49
	v_lshl_add_u64 v[238:239], s[10:11], 0, v[134:135]
	ds_read_b128 v[186:189], v157 offset:32768
	ds_read_b128 v[190:193], v157 offset:33792
	ds_read_b128 v[194:197], v157 offset:34816
	ds_read_b128 v[198:201], v157 offset:35840
	ds_read_b128 v[214:217], v157 offset:36864
	ds_read_b128 v[218:221], v157 offset:37888
	ds_read_b128 v[222:225], v157 offset:38912
	ds_read_b128 v[226:229], v157 offset:39936
	global_load_lds_dwordx4 v[238:239], off
	v_lshl_add_u64 v[238:239], s[10:11], 0, v[132:133]
	s_mov_b32 m0, s50
	s_nop 0
	global_load_lds_dwordx4 v[238:239], off
	s_waitcnt vmcnt(8)
	s_waitcnt lgkmcnt(0)
	s_barrier
	s_setprio 1
	s_waitcnt lgkmcnt(0)
	v_mfma_f32_16x16x32_bf16 v[126:129], v[140:143], v[186:189], v[126:129]
	v_mfma_f32_16x16x32_bf16 v[118:121], v[162:165], v[186:189], v[118:121]
	v_mfma_f32_16x16x32_bf16 v[110:113], v[140:143], v[194:197], v[110:113]
	v_mfma_f32_16x16x32_bf16 v[102:105], v[162:165], v[194:197], v[102:105]
	v_mfma_f32_16x16x32_bf16 v[94:97], v[140:143], v[214:217], v[94:97]
	v_mfma_f32_16x16x32_bf16 v[86:89], v[162:165], v[214:217], v[86:89]
	v_mfma_f32_16x16x32_bf16 v[78:81], v[140:143], v[222:225], v[78:81]
	v_mfma_f32_16x16x32_bf16 v[70:73], v[162:165], v[222:225], v[70:73]
	v_mfma_f32_16x16x32_bf16 v[126:129], v[158:161], v[190:193], v[126:129]
	v_mfma_f32_16x16x32_bf16 v[118:121], v[166:169], v[190:193], v[118:121]
	v_mfma_f32_16x16x32_bf16 v[110:113], v[158:161], v[198:201], v[110:113]
	v_mfma_f32_16x16x32_bf16 v[102:105], v[166:169], v[198:201], v[102:105]
	v_mfma_f32_16x16x32_bf16 v[94:97], v[158:161], v[218:221], v[94:97]
	v_mfma_f32_16x16x32_bf16 v[86:89], v[166:169], v[218:221], v[86:89]
	v_mfma_f32_16x16x32_bf16 v[78:81], v[158:161], v[226:229], v[78:81]
	v_mfma_f32_16x16x32_bf16 v[70:73], v[166:169], v[226:229], v[70:73]
	v_mfma_f32_16x16x32_bf16 v[122:125], v[170:173], v[186:189], v[122:125]
	v_mfma_f32_16x16x32_bf16 v[114:117], v[178:181], v[186:189], v[114:117]
	v_mfma_f32_16x16x32_bf16 v[106:109], v[170:173], v[194:197], v[106:109]
	v_mfma_f32_16x16x32_bf16 v[98:101], v[178:181], v[194:197], v[98:101]
	v_mfma_f32_16x16x32_bf16 v[90:93], v[170:173], v[214:217], v[90:93]
	v_mfma_f32_16x16x32_bf16 v[82:85], v[178:181], v[214:217], v[82:85]
	v_mfma_f32_16x16x32_bf16 v[74:77], v[170:173], v[222:225], v[74:77]
	v_mfma_f32_16x16x32_bf16 v[66:69], v[178:181], v[222:225], v[66:69]
	v_mfma_f32_16x16x32_bf16 v[122:125], v[174:177], v[190:193], v[122:125]
	v_mfma_f32_16x16x32_bf16 v[114:117], v[182:185], v[190:193], v[114:117]
	v_mfma_f32_16x16x32_bf16 v[106:109], v[174:177], v[198:201], v[106:109]
	v_mfma_f32_16x16x32_bf16 v[98:101], v[182:185], v[198:201], v[98:101]
	v_mfma_f32_16x16x32_bf16 v[90:93], v[174:177], v[218:221], v[90:93]
	v_mfma_f32_16x16x32_bf16 v[82:85], v[182:185], v[218:221], v[82:85]
	v_mfma_f32_16x16x32_bf16 v[74:77], v[174:177], v[226:229], v[74:77]
	v_mfma_f32_16x16x32_bf16 v[66:69], v[182:185], v[226:229], v[66:69]
	s_setprio 0
	s_barrier
; #define PG8_STAGE(bufoff, gbase, voff) do { _Pragma("unroll") for (int _i = 0; _i < 2; ++_i) \
;         __builtin_amdgcn_global_load_lds((const unsigned*)((const char*)(gbase) + (voff)[_i]), (PG8_LAS unsigned*)(lds + (bufoff) + ldsw + _i * 8192), 16, 0, 0); } while (0)
; #define PG8_LDA(dst, b, h) do { _Pragma("unroll") for (int m = 0; m < 4; ++m) _Pragma("unroll") for (int k = 0; k < 2; ++k) dst[m][k] = *(const PG8_LAS bf16x8*)(lds + PG8_SA(b, h) + aoff + m * 2048 + k * 1024); } while (0)
; #define PG8_MMA(ai, bj, At, Bt) do { __builtin_amdgcn_s_setprio(1); _Pragma("unroll") for (int m = 0; m < 4; ++m) _Pragma("unroll") for (int n = 0; n < 2; ++n) _Pragma("unroll") for (int k = 0; k < 2; ++k) \
;         acc[ai][bj][m][n] = __builtin_amdgcn_mfma_f32_16x16x32_bf16(Bt[n][k], At[m][k], acc[ai][bj][m][n], 0, 0, 0); __builtin_amdgcn_s_setprio(0); } while (0)
; #define PG8_WAIT_V(n) asm volatile("s_waitcnt vmcnt(" #n ")" ::: "memory")
; #define PG8_WAIT_L(n) asm volatile("s_waitcnt lgkmcnt(" #n ")" ::: "memory")
; #define PG8_BAR __builtin_amdgcn_s_barrier()
; #define PG8_SCHED __builtin_amdgcn_sched_barrier(0)
; template <class Epi, class Sched, bool ALIGN_EPI = false, bool SP2 = false>
; __device__ __forceinline__ void gemm_phase(PG8_LAS unsigned char* lds, const Gemm g, const Sched& S, const Epi& E) {
;     ...
;         for (int t = 0; t < nt; t += 2) {
;     ...
;             PG8_LDA(At, 1, 1); PG8_STAGE(PG8_SB(1, 0), b3, voffB); PG8_STAGE(PG8_SB(1, 1), b3 + hstep, voffB); PG8_STAGE(PG8_SA(1, 0), a3, voffA);
;             PG8_WAIT_V(8); PG8_WAIT_L(0); PG8_BAR; PG8_MMA(1, 0, At, B0); PG8_MMA(1, 1, At, B1); PG8_BAR; PG8_SCHED;
	s_add_i32 s5, s5, s4
	v_lshl_add_u64 v[230:231], v[230:231], 0, s[30:31]
	s_mov_b32 m0, s5
	ds_read_b128 v[186:189], v157 offset:49152
	ds_read_b128 v[190:193], v157 offset:50176
	ds_read_b128 v[194:197], v157 offset:51200
	ds_read_b128 v[198:201], v157 offset:52224
	ds_read_b128 v[214:217], v157 offset:53248
	ds_read_b128 v[218:221], v157 offset:54272
	ds_read_b128 v[222:225], v157 offset:55296
	ds_read_b128 v[226:229], v157 offset:56320
	global_load_lds_dwordx4 v[230:231], off
	s_add_i32 m0, s5, 0x2000
	s_add_u32 s8, s8, 0x40080
	v_lshl_add_u64 v[230:231], v[232:233], 0, s[30:31]
	s_addc_u32 s9, s9, 0
	s_add_i32 s5, s29, s4
	global_load_lds_dwordx4 v[230:231], off
	v_lshl_add_u64 v[230:231], s[8:9], 0, v[0:1]
	s_mov_b32 m0, s5
	s_nop 0
	global_load_lds_dwordx4 v[230:231], off
	v_lshl_add_u64 v[230:231], s[8:9], 0, v[130:131]
	s_add_i32 m0, s5, 0x2000
	s_nop 0
	global_load_lds_dwordx4 v[230:231], off
	v_lshl_add_u64 v[230:231], v[234:235], 0, s[30:31]
	s_mov_b32 m0, s51
	s_nop 0
	global_load_lds_dwordx4 v[230:231], off
	v_lshl_add_u64 v[230:231], v[236:237], 0, s[30:31]
	s_mov_b32 m0, s52
	s_nop 0
	global_load_lds_dwordx4 v[230:231], off
	s_waitcnt vmcnt(8)
	s_waitcnt lgkmcnt(0)
	s_barrier
	s_setprio 1
	s_waitcnt lgkmcnt(0)
	v_mfma_f32_16x16x32_bf16 v[62:65], v[140:143], v[186:189], v[62:65]
	v_mfma_f32_16x16x32_bf16 v[54:57], v[162:165], v[186:189], v[54:57]
	v_mfma_f32_16x16x32_bf16 v[46:49], v[140:143], v[194:197], v[46:49]
	v_mfma_f32_16x16x32_bf16 v[38:41], v[162:165], v[194:197], v[38:41]
	v_mfma_f32_16x16x32_bf16 v[30:33], v[140:143], v[214:217], v[30:33]
	v_mfma_f32_16x16x32_bf16 v[22:25], v[162:165], v[214:217], v[22:25]
	v_mfma_f32_16x16x32_bf16 v[14:17], v[140:143], v[222:225], v[14:17]
	v_mfma_f32_16x16x32_bf16 v[6:9], v[162:165], v[222:225], v[6:9]
	v_mfma_f32_16x16x32_bf16 v[62:65], v[158:161], v[190:193], v[62:65]
	v_mfma_f32_16x16x32_bf16 v[54:57], v[166:169], v[190:193], v[54:57]
	v_mfma_f32_16x16x32_bf16 v[46:49], v[158:161], v[198:201], v[46:49]
	v_mfma_f32_16x16x32_bf16 v[38:41], v[166:169], v[198:201], v[38:41]
	v_mfma_f32_16x16x32_bf16 v[30:33], v[158:161], v[218:221], v[30:33]
	v_mfma_f32_16x16x32_bf16 v[22:25], v[166:169], v[218:221], v[22:25]
	v_mfma_f32_16x16x32_bf16 v[14:17], v[158:161], v[226:229], v[14:17]
	v_mfma_f32_16x16x32_bf16 v[6:9], v[166:169], v[226:229], v[6:9]
	v_mfma_f32_16x16x32_bf16 v[58:61], v[170:173], v[186:189], v[58:61]
	v_mfma_f32_16x16x32_bf16 v[50:53], v[178:181], v[186:189], v[50:53]
	v_mfma_f32_16x16x32_bf16 v[42:45], v[170:173], v[194:197], v[42:45]
	v_mfma_f32_16x16x32_bf16 v[34:37], v[178:181], v[194:197], v[34:37]
	v_mfma_f32_16x16x32_bf16 v[26:29], v[170:173], v[214:217], v[26:29]
	v_mfma_f32_16x16x32_bf16 v[18:21], v[178:181], v[214:217], v[18:21]
	v_mfma_f32_16x16x32_bf16 v[10:13], v[170:173], v[222:225], v[10:13]
	v_mfma_f32_16x16x32_bf16 v[2:5], v[178:181], v[222:225], v[2:5]
	v_mfma_f32_16x16x32_bf16 v[58:61], v[174:177], v[190:193], v[58:61]
	v_mfma_f32_16x16x32_bf16 v[50:53], v[182:185], v[190:193], v[50:53]
	v_mfma_f32_16x16x32_bf16 v[42:45], v[174:177], v[198:201], v[42:45]
	v_mfma_f32_16x16x32_bf16 v[34:37], v[182:185], v[198:201], v[34:37]
	v_mfma_f32_16x16x32_bf16 v[26:29], v[174:177], v[218:221], v[26:29]
	v_mfma_f32_16x16x32_bf16 v[18:21], v[182:185], v[218:221], v[18:21]
	v_mfma_f32_16x16x32_bf16 v[10:13], v[174:177], v[226:229], v[10:13]
	v_mfma_f32_16x16x32_bf16 v[2:5], v[182:185], v[226:229], v[2:5]
	s_setprio 0
	s_barrier
	s_add_i32 s58, s58, 2
	s_add_u32 s2, s2, 0x100
	s_addc_u32 s3, s3, 0
	s_add_u32 s56, s56, 0x100
	s_addc_u32 s57, s57, 0
	s_cmp_gt_u32 s58, 13
	s_cbranch_scc0 .LBB0_663
	s_and_b64 vcc, exec, s[38:39]
	s_cbranch_vccz .LBB0_666
	s_barrier
